# gate|up epilogue reads its eight row scales from LDS together (two wait states kept after each tile store)
# speedup vs baseline: 1.0057x; 1.0057x over previous
.LBB11_2572:
	s_or_b64 exec, exec, s[26:27]
	s_lshl_b32 s0, s42, 10
	v_mov_b32_e32 v148, v143
	v_mov_b32_e32 v149, v141
	s_add_i32 s0, s0, 0
	s_xor_b32 s42, s42, 1
	v_lshl_add_u32 v147, v149, 2, s0
	v_add_u32_e32 v147, 0x22000, v147
	ds_read_b32 v150, v147
	ds_read_b32 v170, v147 offset:64
	ds_read_b32 v172, v147 offset:128
	ds_read_b32 v174, v147 offset:192
	ds_read_b32 v176, v147 offset:512
	ds_read_b32 v178, v147 offset:576
	ds_read_b32 v180, v147 offset:640
	ds_read_b32 v190, v147 offset:704
	s_movk_i32 s0, 0xb00
	s_waitcnt lgkmcnt(0)
	v_mul_f32_e32 v152, 0xbfb8aa3b, v150
	v_pk_mul_f32 v[154:155], v[126:127], v[152:153] op_sel_hi:[1,0]
	v_pk_mul_f32 v[126:127], v[126:127], v[150:151] op_sel_hi:[1,0]
	v_pk_mul_f32 v[122:123], v[122:123], v[150:151] op_sel_hi:[1,0]
	v_pk_mul_f32 v[124:125], v[124:125], v[150:151] op_sel_hi:[1,0]
	v_pk_mul_f32 v[122:123], v[126:127], v[122:123]
	v_pk_mul_f32 v[126:127], v[128:129], v[152:153] op_sel_hi:[1,0]
	v_pk_mul_f32 v[128:129], v[128:129], v[150:151] op_sel_hi:[1,0]
	v_exp_f32_e32 v126, v126
	v_exp_f32_e32 v127, v127
	v_pk_mul_f32 v[124:125], v[128:129], v[124:125]
	v_pk_mul_f32 v[114:115], v[114:115], v[150:151] op_sel_hi:[1,0]
	v_exp_f32_e32 v154, v154
	v_pk_add_f32 v[126:127], v[126:127], 1.0 op_sel_hi:[1,0]
	v_exp_f32_e32 v155, v155
	v_rcp_f32_e32 v126, v126
	v_rcp_f32_e32 v127, v127
	v_pk_mul_f32 v[116:117], v[116:117], v[150:151] op_sel_hi:[1,0]
	v_pk_add_f32 v[154:155], v[154:155], 1.0 op_sel_hi:[1,0]
	v_pk_mul_f32 v[124:125], v[124:125], v[126:127]
	v_pk_mul_f32 v[126:127], v[118:119], v[152:153] op_sel_hi:[1,0]
	v_pk_mul_f32 v[118:119], v[118:119], v[150:151] op_sel_hi:[1,0]
	v_exp_f32_e32 v126, v126
	v_exp_f32_e32 v127, v127
	v_pk_mul_f32 v[114:115], v[118:119], v[114:115]
	v_pk_mul_f32 v[118:119], v[120:121], v[152:153] op_sel_hi:[1,0]
	v_rcp_f32_e32 v154, v154
	v_exp_f32_e32 v118, v118
	v_exp_f32_e32 v119, v119
	v_pk_add_f32 v[126:127], v[126:127], 1.0 op_sel_hi:[1,0]
	v_rcp_f32_e32 v155, v155
	v_rcp_f32_e32 v126, v126
	v_rcp_f32_e32 v127, v127
	v_pk_add_f32 v[118:119], v[118:119], 1.0 op_sel_hi:[1,0]
	v_pk_mul_f32 v[120:121], v[120:121], v[150:151] op_sel_hi:[1,0]
	v_rcp_f32_e32 v118, v118
	v_rcp_f32_e32 v119, v119
	v_pk_mul_f32 v[114:115], v[114:115], v[126:127]
	v_pk_mul_f32 v[116:117], v[120:121], v[116:117]
	v_lshl_add_u32 v126, s7, 8, v149
	v_pk_mul_f32 v[122:123], v[122:123], v[154:155]
	v_pk_mul_f32 v[120:121], v[116:117], v[118:119]
	v_cvt_pk_bf16_f32 v116, v122, v123
	v_cvt_pk_bf16_f32 v117, v124, v125
	v_cvt_pk_bf16_f32 v118, v114, v115
	v_mad_u64_u32 v[114:115], s[0:1], v126, s0, v[148:149]
	s_lshl_b32 s0, s6, 8
	s_nop 0
	v_lshl_add_u32 v114, v114, 1, s0
	v_cvt_pk_bf16_f32 v119, v120, v121
	buffer_store_dwordx4 v[116:119], v114, s[52:55], 0 offen sc1
	s_nop 1
	v_pk_mul_f32 v[106:107], v[106:107], v[170:171] op_sel_hi:[1,0]
	v_mul_f32_e32 v118, 0xbfb8aa3b, v170
	v_pk_mul_f32 v[120:121], v[110:111], v[118:119] op_sel_hi:[1,0]
	v_pk_mul_f32 v[110:111], v[110:111], v[170:171] op_sel_hi:[1,0]
	v_pk_mul_f32 v[108:109], v[108:109], v[170:171] op_sel_hi:[1,0]
	v_pk_mul_f32 v[106:107], v[110:111], v[106:107]
	v_pk_mul_f32 v[110:111], v[112:113], v[118:119] op_sel_hi:[1,0]
	v_pk_mul_f32 v[112:113], v[112:113], v[170:171] op_sel_hi:[1,0]
	v_exp_f32_e32 v110, v110
	v_exp_f32_e32 v111, v111
	v_pk_mul_f32 v[108:109], v[112:113], v[108:109]
	v_pk_mul_f32 v[98:99], v[98:99], v[170:171] op_sel_hi:[1,0]
	v_exp_f32_e32 v120, v120
	v_pk_add_f32 v[110:111], v[110:111], 1.0 op_sel_hi:[1,0]
	v_exp_f32_e32 v121, v121
	v_rcp_f32_e32 v110, v110
	v_rcp_f32_e32 v111, v111
	v_pk_mul_f32 v[100:101], v[100:101], v[170:171] op_sel_hi:[1,0]
	v_pk_add_f32 v[120:121], v[120:121], 1.0 op_sel_hi:[1,0]
	v_pk_mul_f32 v[108:109], v[108:109], v[110:111]
	v_pk_mul_f32 v[110:111], v[102:103], v[118:119] op_sel_hi:[1,0]
	v_pk_mul_f32 v[102:103], v[102:103], v[170:171] op_sel_hi:[1,0]
	v_exp_f32_e32 v110, v110
	v_exp_f32_e32 v111, v111
	v_pk_mul_f32 v[98:99], v[102:103], v[98:99]
	v_rcp_f32_e32 v120, v120
	v_rcp_f32_e32 v121, v121
	v_pk_add_f32 v[110:111], v[110:111], 1.0 op_sel_hi:[1,0]
	v_pk_mul_f32 v[106:107], v[106:107], v[120:121]
	v_rcp_f32_e32 v110, v110
	v_rcp_f32_e32 v111, v111
	s_nop 0
	v_pk_mul_f32 v[102:103], v[98:99], v[110:111]
	v_pk_mul_f32 v[98:99], v[104:105], v[118:119] op_sel_hi:[1,0]
	v_pk_mul_f32 v[104:105], v[104:105], v[170:171] op_sel_hi:[1,0]
	v_exp_f32_e32 v98, v98
	v_exp_f32_e32 v99, v99
	v_pk_mul_f32 v[100:101], v[104:105], v[100:101]
	v_pk_add_f32 v[98:99], v[98:99], 1.0 op_sel_hi:[1,0]
	s_nop 0
	v_rcp_f32_e32 v98, v98
	v_rcp_f32_e32 v99, v99
	s_nop 0
	v_pk_mul_f32 v[104:105], v[100:101], v[98:99]
	v_cvt_pk_bf16_f32 v98, v106, v107
	v_cvt_pk_bf16_f32 v99, v108, v109
	v_cvt_pk_bf16_f32 v100, v102, v103
	v_add_u32_e32 v102, 0x16000, v114
	v_cvt_pk_bf16_f32 v101, v104, v105
	buffer_store_dwordx4 v[98:101], v102, s[52:55], 0 offen sc1
	s_nop 1
	v_pk_mul_f32 v[90:91], v[90:91], v[172:173] op_sel_hi:[1,0]
	v_mul_f32_e32 v100, 0xbfb8aa3b, v172
	v_pk_mul_f32 v[102:103], v[94:95], v[100:101] op_sel_hi:[1,0]
	v_pk_mul_f32 v[94:95], v[94:95], v[172:173] op_sel_hi:[1,0]
	v_pk_mul_f32 v[92:93], v[92:93], v[172:173] op_sel_hi:[1,0]
	v_pk_mul_f32 v[90:91], v[94:95], v[90:91]
	v_pk_mul_f32 v[94:95], v[96:97], v[100:101] op_sel_hi:[1,0]
	v_pk_mul_f32 v[96:97], v[96:97], v[172:173] op_sel_hi:[1,0]
	v_exp_f32_e32 v94, v94
	v_exp_f32_e32 v95, v95
	v_pk_mul_f32 v[92:93], v[96:97], v[92:93]
	v_pk_mul_f32 v[82:83], v[82:83], v[172:173] op_sel_hi:[1,0]
	v_exp_f32_e32 v102, v102
	v_pk_add_f32 v[94:95], v[94:95], 1.0 op_sel_hi:[1,0]
	v_exp_f32_e32 v103, v103
	v_rcp_f32_e32 v94, v94
	v_rcp_f32_e32 v95, v95
	v_pk_mul_f32 v[84:85], v[84:85], v[172:173] op_sel_hi:[1,0]
	v_pk_add_f32 v[102:103], v[102:103], 1.0 op_sel_hi:[1,0]
	v_pk_mul_f32 v[92:93], v[92:93], v[94:95]
	v_pk_mul_f32 v[94:95], v[86:87], v[100:101] op_sel_hi:[1,0]
	v_pk_mul_f32 v[86:87], v[86:87], v[172:173] op_sel_hi:[1,0]
	v_exp_f32_e32 v94, v94
	v_exp_f32_e32 v95, v95
	v_pk_mul_f32 v[82:83], v[86:87], v[82:83]
	v_rcp_f32_e32 v102, v102
	v_rcp_f32_e32 v103, v103
	v_pk_add_f32 v[94:95], v[94:95], 1.0 op_sel_hi:[1,0]
	v_pk_mul_f32 v[90:91], v[90:91], v[102:103]
	v_rcp_f32_e32 v94, v94
	v_rcp_f32_e32 v95, v95
	s_nop 0
	v_pk_mul_f32 v[86:87], v[82:83], v[94:95]
	v_pk_mul_f32 v[82:83], v[88:89], v[100:101] op_sel_hi:[1,0]
	v_pk_mul_f32 v[88:89], v[88:89], v[172:173] op_sel_hi:[1,0]
	v_exp_f32_e32 v82, v82
	v_exp_f32_e32 v83, v83
	v_pk_mul_f32 v[84:85], v[88:89], v[84:85]
	v_pk_add_f32 v[82:83], v[82:83], 1.0 op_sel_hi:[1,0]
	s_nop 0
	v_rcp_f32_e32 v82, v82
	v_rcp_f32_e32 v83, v83
	s_nop 0
	v_pk_mul_f32 v[88:89], v[84:85], v[82:83]
	v_cvt_pk_bf16_f32 v82, v90, v91
	v_cvt_pk_bf16_f32 v83, v92, v93
	v_cvt_pk_bf16_f32 v84, v86, v87
	v_add_u32_e32 v86, 0x2c000, v114
	v_cvt_pk_bf16_f32 v85, v88, v89
	buffer_store_dwordx4 v[82:85], v86, s[52:55], 0 offen sc1
	s_nop 1
	v_pk_mul_f32 v[74:75], v[74:75], v[174:175] op_sel_hi:[1,0]
	v_mul_f32_e32 v84, 0xbfb8aa3b, v174
	v_pk_mul_f32 v[86:87], v[78:79], v[84:85] op_sel_hi:[1,0]
	v_pk_mul_f32 v[78:79], v[78:79], v[174:175] op_sel_hi:[1,0]
	v_pk_mul_f32 v[76:77], v[76:77], v[174:175] op_sel_hi:[1,0]
	v_pk_mul_f32 v[74:75], v[78:79], v[74:75]
	v_pk_mul_f32 v[78:79], v[80:81], v[84:85] op_sel_hi:[1,0]
	v_pk_mul_f32 v[80:81], v[80:81], v[174:175] op_sel_hi:[1,0]
	v_exp_f32_e32 v78, v78
	v_exp_f32_e32 v79, v79
	v_pk_mul_f32 v[76:77], v[80:81], v[76:77]
	v_pk_mul_f32 v[66:67], v[66:67], v[174:175] op_sel_hi:[1,0]
	v_exp_f32_e32 v86, v86
	v_pk_add_f32 v[78:79], v[78:79], 1.0 op_sel_hi:[1,0]
	v_exp_f32_e32 v87, v87
	v_rcp_f32_e32 v78, v78
	v_rcp_f32_e32 v79, v79
	v_pk_mul_f32 v[68:69], v[68:69], v[174:175] op_sel_hi:[1,0]
	v_pk_add_f32 v[86:87], v[86:87], 1.0 op_sel_hi:[1,0]
	v_pk_mul_f32 v[76:77], v[76:77], v[78:79]
	v_pk_mul_f32 v[78:79], v[70:71], v[84:85] op_sel_hi:[1,0]
	v_pk_mul_f32 v[70:71], v[70:71], v[174:175] op_sel_hi:[1,0]
	v_exp_f32_e32 v78, v78
	v_exp_f32_e32 v79, v79
	v_pk_mul_f32 v[66:67], v[70:71], v[66:67]
	v_rcp_f32_e32 v86, v86
	v_rcp_f32_e32 v87, v87
	v_pk_add_f32 v[78:79], v[78:79], 1.0 op_sel_hi:[1,0]
	v_pk_mul_f32 v[74:75], v[74:75], v[86:87]
	v_rcp_f32_e32 v78, v78
	v_rcp_f32_e32 v79, v79
	s_nop 0
	v_pk_mul_f32 v[70:71], v[66:67], v[78:79]
	v_pk_mul_f32 v[66:67], v[72:73], v[84:85] op_sel_hi:[1,0]
	v_pk_mul_f32 v[72:73], v[72:73], v[174:175] op_sel_hi:[1,0]
	v_exp_f32_e32 v66, v66
	v_exp_f32_e32 v67, v67
	v_pk_mul_f32 v[68:69], v[72:73], v[68:69]
	v_pk_add_f32 v[66:67], v[66:67], 1.0 op_sel_hi:[1,0]
	s_nop 0
	v_rcp_f32_e32 v66, v66
	v_rcp_f32_e32 v67, v67
	s_nop 0
	v_pk_mul_f32 v[72:73], v[68:69], v[66:67]
	v_cvt_pk_bf16_f32 v66, v74, v75
	v_cvt_pk_bf16_f32 v67, v76, v77
	v_cvt_pk_bf16_f32 v68, v70, v71
	v_add_u32_e32 v70, 0x42000, v114
	v_cvt_pk_bf16_f32 v69, v72, v73
	buffer_store_dwordx4 v[66:69], v70, s[52:55], 0 offen sc1
	s_nop 1
	v_pk_mul_f32 v[58:59], v[58:59], v[176:177] op_sel_hi:[1,0]
	v_mul_f32_e32 v68, 0xbfb8aa3b, v176
	v_pk_mul_f32 v[70:71], v[62:63], v[68:69] op_sel_hi:[1,0]
	v_pk_mul_f32 v[62:63], v[62:63], v[176:177] op_sel_hi:[1,0]
	v_pk_mul_f32 v[60:61], v[60:61], v[176:177] op_sel_hi:[1,0]
	v_pk_mul_f32 v[58:59], v[62:63], v[58:59]
	v_pk_mul_f32 v[62:63], v[64:65], v[68:69] op_sel_hi:[1,0]
	v_pk_mul_f32 v[64:65], v[64:65], v[176:177] op_sel_hi:[1,0]
	v_exp_f32_e32 v62, v62
	v_exp_f32_e32 v63, v63
	v_pk_mul_f32 v[60:61], v[64:65], v[60:61]
	v_pk_mul_f32 v[50:51], v[50:51], v[176:177] op_sel_hi:[1,0]
	v_exp_f32_e32 v70, v70
	v_pk_add_f32 v[62:63], v[62:63], 1.0 op_sel_hi:[1,0]
	v_exp_f32_e32 v71, v71
	v_rcp_f32_e32 v62, v62
	v_rcp_f32_e32 v63, v63
	v_pk_mul_f32 v[52:53], v[52:53], v[176:177] op_sel_hi:[1,0]
	v_pk_add_f32 v[70:71], v[70:71], 1.0 op_sel_hi:[1,0]
	v_pk_mul_f32 v[60:61], v[60:61], v[62:63]
	v_pk_mul_f32 v[62:63], v[54:55], v[68:69] op_sel_hi:[1,0]
	v_pk_mul_f32 v[54:55], v[54:55], v[176:177] op_sel_hi:[1,0]
	v_exp_f32_e32 v62, v62
	v_exp_f32_e32 v63, v63
	v_pk_mul_f32 v[50:51], v[54:55], v[50:51]
	v_rcp_f32_e32 v70, v70
	v_rcp_f32_e32 v71, v71
	v_pk_add_f32 v[62:63], v[62:63], 1.0 op_sel_hi:[1,0]
	v_pk_mul_f32 v[58:59], v[58:59], v[70:71]
	v_rcp_f32_e32 v62, v62
	v_rcp_f32_e32 v63, v63
	s_nop 0
	v_pk_mul_f32 v[54:55], v[50:51], v[62:63]
	v_pk_mul_f32 v[50:51], v[56:57], v[68:69] op_sel_hi:[1,0]
	v_pk_mul_f32 v[56:57], v[56:57], v[176:177] op_sel_hi:[1,0]
	v_exp_f32_e32 v50, v50
	v_exp_f32_e32 v51, v51
	v_pk_mul_f32 v[52:53], v[56:57], v[52:53]
	v_pk_add_f32 v[50:51], v[50:51], 1.0 op_sel_hi:[1,0]
	s_nop 0
	v_rcp_f32_e32 v50, v50
	v_rcp_f32_e32 v51, v51
	s_nop 0
	v_pk_mul_f32 v[56:57], v[52:53], v[50:51]
	v_cvt_pk_bf16_f32 v50, v58, v59
	v_cvt_pk_bf16_f32 v51, v60, v61
	v_cvt_pk_bf16_f32 v52, v54, v55
	v_add_u32_e32 v54, 0xb0000, v114
	v_cvt_pk_bf16_f32 v53, v56, v57
	buffer_store_dwordx4 v[50:53], v54, s[52:55], 0 offen sc1
	s_nop 1
	v_pk_mul_f32 v[42:43], v[42:43], v[178:179] op_sel_hi:[1,0]
	v_mul_f32_e32 v52, 0xbfb8aa3b, v178
	v_pk_mul_f32 v[54:55], v[46:47], v[52:53] op_sel_hi:[1,0]
	v_pk_mul_f32 v[46:47], v[46:47], v[178:179] op_sel_hi:[1,0]
	v_pk_mul_f32 v[44:45], v[44:45], v[178:179] op_sel_hi:[1,0]
	v_pk_mul_f32 v[42:43], v[46:47], v[42:43]
	v_pk_mul_f32 v[46:47], v[48:49], v[52:53] op_sel_hi:[1,0]
	v_pk_mul_f32 v[48:49], v[48:49], v[178:179] op_sel_hi:[1,0]
	v_exp_f32_e32 v46, v46
	v_exp_f32_e32 v47, v47
	v_pk_mul_f32 v[44:45], v[48:49], v[44:45]
	v_pk_mul_f32 v[34:35], v[34:35], v[178:179] op_sel_hi:[1,0]
	v_exp_f32_e32 v54, v54
	v_pk_add_f32 v[46:47], v[46:47], 1.0 op_sel_hi:[1,0]
	v_exp_f32_e32 v55, v55
	v_rcp_f32_e32 v46, v46
	v_rcp_f32_e32 v47, v47
	v_pk_mul_f32 v[36:37], v[36:37], v[178:179] op_sel_hi:[1,0]
	v_pk_add_f32 v[54:55], v[54:55], 1.0 op_sel_hi:[1,0]
	v_pk_mul_f32 v[44:45], v[44:45], v[46:47]
	v_pk_mul_f32 v[46:47], v[38:39], v[52:53] op_sel_hi:[1,0]
	v_pk_mul_f32 v[38:39], v[38:39], v[178:179] op_sel_hi:[1,0]
	v_exp_f32_e32 v46, v46
	v_exp_f32_e32 v47, v47
	v_pk_mul_f32 v[34:35], v[38:39], v[34:35]
	v_rcp_f32_e32 v54, v54
	v_rcp_f32_e32 v55, v55
	v_pk_add_f32 v[46:47], v[46:47], 1.0 op_sel_hi:[1,0]
	v_pk_mul_f32 v[42:43], v[42:43], v[54:55]
	v_rcp_f32_e32 v46, v46
	v_rcp_f32_e32 v47, v47
	s_nop 0
	v_pk_mul_f32 v[38:39], v[34:35], v[46:47]
	v_pk_mul_f32 v[34:35], v[40:41], v[52:53] op_sel_hi:[1,0]
	v_pk_mul_f32 v[40:41], v[40:41], v[178:179] op_sel_hi:[1,0]
	v_exp_f32_e32 v34, v34
	v_exp_f32_e32 v35, v35
	v_pk_mul_f32 v[36:37], v[40:41], v[36:37]
	v_pk_add_f32 v[34:35], v[34:35], 1.0 op_sel_hi:[1,0]
	s_nop 0
	v_rcp_f32_e32 v34, v34
	v_rcp_f32_e32 v35, v35
	s_nop 0
	v_pk_mul_f32 v[40:41], v[36:37], v[34:35]
	v_cvt_pk_bf16_f32 v34, v42, v43
	v_cvt_pk_bf16_f32 v35, v44, v45
	v_cvt_pk_bf16_f32 v36, v38, v39
	v_add_u32_e32 v38, 0xc6000, v114
	v_cvt_pk_bf16_f32 v37, v40, v41
	buffer_store_dwordx4 v[34:37], v38, s[52:55], 0 offen sc1
	s_nop 1
	v_pk_mul_f32 v[26:27], v[26:27], v[180:181] op_sel_hi:[1,0]
	v_mul_f32_e32 v36, 0xbfb8aa3b, v180
	v_pk_mul_f32 v[38:39], v[30:31], v[36:37] op_sel_hi:[1,0]
	v_pk_mul_f32 v[30:31], v[30:31], v[180:181] op_sel_hi:[1,0]
	v_pk_mul_f32 v[28:29], v[28:29], v[180:181] op_sel_hi:[1,0]
	v_pk_mul_f32 v[26:27], v[30:31], v[26:27]
	v_pk_mul_f32 v[30:31], v[32:33], v[36:37] op_sel_hi:[1,0]
	v_pk_mul_f32 v[32:33], v[32:33], v[180:181] op_sel_hi:[1,0]
	v_exp_f32_e32 v30, v30
	v_exp_f32_e32 v31, v31
	v_pk_mul_f32 v[28:29], v[32:33], v[28:29]
	v_pk_mul_f32 v[18:19], v[18:19], v[180:181] op_sel_hi:[1,0]
	v_exp_f32_e32 v38, v38
	v_pk_add_f32 v[30:31], v[30:31], 1.0 op_sel_hi:[1,0]
	v_exp_f32_e32 v39, v39
	v_rcp_f32_e32 v30, v30
	v_rcp_f32_e32 v31, v31
	v_pk_mul_f32 v[20:21], v[20:21], v[180:181] op_sel_hi:[1,0]
	v_pk_add_f32 v[38:39], v[38:39], 1.0 op_sel_hi:[1,0]
	v_pk_mul_f32 v[28:29], v[28:29], v[30:31]
	v_pk_mul_f32 v[30:31], v[22:23], v[36:37] op_sel_hi:[1,0]
	v_pk_mul_f32 v[22:23], v[22:23], v[180:181] op_sel_hi:[1,0]
	v_exp_f32_e32 v30, v30
	v_exp_f32_e32 v31, v31
	v_pk_mul_f32 v[18:19], v[22:23], v[18:19]
	v_rcp_f32_e32 v38, v38
	v_rcp_f32_e32 v39, v39
	v_pk_add_f32 v[30:31], v[30:31], 1.0 op_sel_hi:[1,0]
	v_pk_mul_f32 v[26:27], v[26:27], v[38:39]
	v_rcp_f32_e32 v30, v30
	v_rcp_f32_e32 v31, v31
	s_nop 0
	v_pk_mul_f32 v[22:23], v[18:19], v[30:31]
	v_pk_mul_f32 v[18:19], v[24:25], v[36:37] op_sel_hi:[1,0]
	v_pk_mul_f32 v[24:25], v[24:25], v[180:181] op_sel_hi:[1,0]
	v_exp_f32_e32 v18, v18
	v_exp_f32_e32 v19, v19
	v_pk_mul_f32 v[20:21], v[24:25], v[20:21]
	v_pk_add_f32 v[18:19], v[18:19], 1.0 op_sel_hi:[1,0]
	s_nop 0
	v_rcp_f32_e32 v18, v18
	v_rcp_f32_e32 v19, v19
	s_nop 0
	v_pk_mul_f32 v[24:25], v[20:21], v[18:19]
	v_cvt_pk_bf16_f32 v18, v26, v27
	v_cvt_pk_bf16_f32 v19, v28, v29
	v_cvt_pk_bf16_f32 v20, v22, v23
	v_add_u32_e32 v22, 0xdc000, v114
	v_cvt_pk_bf16_f32 v21, v24, v25
	buffer_store_dwordx4 v[18:21], v22, s[52:55], 0 offen sc1
	s_nop 1
	v_pk_mul_f32 v[10:11], v[10:11], v[190:191] op_sel_hi:[1,0]
	v_mul_f32_e32 v20, 0xbfb8aa3b, v190
	v_pk_mul_f32 v[22:23], v[14:15], v[20:21] op_sel_hi:[1,0]
	v_pk_mul_f32 v[14:15], v[14:15], v[190:191] op_sel_hi:[1,0]
	v_pk_mul_f32 v[12:13], v[12:13], v[190:191] op_sel_hi:[1,0]
	v_pk_mul_f32 v[10:11], v[14:15], v[10:11]
	v_pk_mul_f32 v[14:15], v[16:17], v[20:21] op_sel_hi:[1,0]
	v_pk_mul_f32 v[16:17], v[16:17], v[190:191] op_sel_hi:[1,0]
	v_exp_f32_e32 v14, v14
	v_exp_f32_e32 v15, v15
	v_pk_mul_f32 v[12:13], v[16:17], v[12:13]
	v_pk_mul_f32 v[2:3], v[2:3], v[190:191] op_sel_hi:[1,0]
	v_exp_f32_e32 v22, v22
	v_pk_add_f32 v[14:15], v[14:15], 1.0 op_sel_hi:[1,0]
	v_exp_f32_e32 v23, v23
	v_rcp_f32_e32 v14, v14
	v_rcp_f32_e32 v15, v15
	v_pk_mul_f32 v[4:5], v[4:5], v[190:191] op_sel_hi:[1,0]
	v_pk_add_f32 v[22:23], v[22:23], 1.0 op_sel_hi:[1,0]
	v_pk_mul_f32 v[12:13], v[12:13], v[14:15]
	v_pk_mul_f32 v[14:15], v[6:7], v[20:21] op_sel_hi:[1,0]
	v_pk_mul_f32 v[6:7], v[6:7], v[190:191] op_sel_hi:[1,0]
	v_exp_f32_e32 v14, v14
	v_exp_f32_e32 v15, v15
	v_pk_mul_f32 v[2:3], v[6:7], v[2:3]
	v_rcp_f32_e32 v22, v22
	v_rcp_f32_e32 v23, v23
	v_pk_add_f32 v[14:15], v[14:15], 1.0 op_sel_hi:[1,0]
	v_pk_mul_f32 v[10:11], v[10:11], v[22:23]
	v_rcp_f32_e32 v14, v14
	v_rcp_f32_e32 v15, v15
	s_nop 0
	v_pk_mul_f32 v[6:7], v[2:3], v[14:15]
	v_pk_mul_f32 v[2:3], v[8:9], v[20:21] op_sel_hi:[1,0]
	v_pk_mul_f32 v[8:9], v[8:9], v[190:191] op_sel_hi:[1,0]
	v_exp_f32_e32 v2, v2
	v_exp_f32_e32 v3, v3
	v_pk_mul_f32 v[4:5], v[8:9], v[4:5]
	v_pk_add_f32 v[2:3], v[2:3], 1.0 op_sel_hi:[1,0]
	s_nop 0
	v_rcp_f32_e32 v2, v2
	v_rcp_f32_e32 v3, v3
	s_nop 0
	v_pk_mul_f32 v[8:9], v[4:5], v[2:3]
	v_cvt_pk_bf16_f32 v2, v10, v11
	v_cvt_pk_bf16_f32 v3, v12, v13
	v_cvt_pk_bf16_f32 v4, v6, v7
	v_add_u32_e32 v6, 0xf2000, v114
	v_cvt_pk_bf16_f32 v5, v8, v9
	buffer_store_dwordx4 v[2:5], v6, s[52:55], 0 offen sc1
	s_and_saveexec_b64 s[26:27], s[10:11]
	s_cbranch_execz .LBB11_2574
	s_waitcnt vmcnt(8)
	v_fmamk_f32 v146, v146, 0x3a800000, v206
	v_mul_f32_e32 v2, 0x4b800000, v146
	v_cmp_gt_f32_e32 vcc, s77, v146
	s_nop 1
	v_cndmask_b32_e32 v2, v146, v2, vcc
	v_rsq_f32_e32 v2, v2
	s_nop 0
	v_mul_f32_e32 v3, 0x45800000, v2
	v_cndmask_b32_e32 v2, v2, v3, vcc
	v_lshl_add_u32 v3, s42, 10, v144
	ds_write_b32 v3, v2
